# no L2 write-back at the two barriers whose producing phase now writes everything through (after out-projection l0 and after pre-norm l1)
# speedup vs baseline: 1.0151x; 1.0029x over previous
; __device__ __forceinline__ void fast_grid_barrier(unsigned* base, int seam, int tid) {
;     asm volatile("s_waitcnt vmcnt(0)" ::: "memory");
;     __syncthreads();
;     if (tid == 0) {
;         unsigned* cnt = base + seam * 128;
;         unsigned* flg = cnt + 64;
;         __builtin_amdgcn_fence(__ATOMIC_RELEASE, "agent");
;         asm volatile("s_waitcnt vmcnt(0)" ::: "memory");
;         const unsigned old = __hip_atomic_fetch_add(cnt, 1u, __ATOMIC_RELAXED, __HIP_MEMORY_SCOPE_AGENT);
;         if (old == gridDim.x - 1) __hip_atomic_store(flg, 1u, __ATOMIC_RELAXED, __HIP_MEMORY_SCOPE_AGENT);
;         else { unsigned sp = 0; while (__hip_atomic_load(flg, __ATOMIC_RELAXED, __HIP_MEMORY_SCOPE_AGENT) == 0u) { __builtin_amdgcn_s_sleep(2); if (++sp > (1u << 22)) break; } }
;         __builtin_amdgcn_fence(__ATOMIC_ACQUIRE, "agent");
;         asm volatile("s_waitcnt vmcnt(0)" ::: "memory");
;     }
;     __syncthreads();
.LBB0_586:
	s_waitcnt lgkmcnt(0)
	s_cmp_lt_i32 s47, 6
	s_cbranch_scc1 .LBB0_603
	s_waitcnt vmcnt(0)
	v_cmp_eq_u32_e32 vcc, 0, v202
	s_barrier
	s_and_saveexec_b64 s[0:1], vcc
	s_cbranch_execz .LBB0_602
	s_load_dwordx2 s[4:5], s[84:85], 0x90
	s_lshl_b32 s3, s98, 6
	v_mov_b32_e32 v0, s3
	v_mov_b32_e32 v2, 1
	s_waitcnt lgkmcnt(0)
	s_add_u32 s4, s4, 0x1400
	s_addc_u32 s5, s5, 0
	global_atomic_add v1, v0, v2, s[4:5] offset:128 sc0
	s_mul_i32 s6, s99, 4
	s_add_i32 s3, s6, -1
	s_lshl_b32 s6, s98, 6
	s_sub_u32 s6, s4, s6
	s_subb_u32 s7, s5, 0
	s_mul_i32 s4, s100, 4
	s_waitcnt vmcnt(0)
	v_cmp_ne_u32_e32 vcc, s3, v1
	s_cbranch_vccnz .Lsm4_wtop
	global_atomic_add v0, v2, s[6:7] offset:2176

; __device__ __forceinline__ void fast_grid_barrier(unsigned* base, int seam, int tid) {
;     asm volatile("s_waitcnt vmcnt(0)" ::: "memory");
;     __syncthreads();
;     if (tid == 0) {
;         unsigned* cnt = base + seam * 128;
;         unsigned* flg = cnt + 64;
;         __builtin_amdgcn_fence(__ATOMIC_RELEASE, "agent");
;         asm volatile("s_waitcnt vmcnt(0)" ::: "memory");
;         const unsigned old = __hip_atomic_fetch_add(cnt, 1u, __ATOMIC_RELAXED, __HIP_MEMORY_SCOPE_AGENT);
;         if (old == gridDim.x - 1) __hip_atomic_store(flg, 1u, __ATOMIC_RELAXED, __HIP_MEMORY_SCOPE_AGENT);
;         else { unsigned sp = 0; while (__hip_atomic_load(flg, __ATOMIC_RELAXED, __HIP_MEMORY_SCOPE_AGENT) == 0u) { __builtin_amdgcn_s_sleep(2); if (++sp > (1u << 22)) break; } }
;         __builtin_amdgcn_fence(__ATOMIC_ACQUIRE, "agent");
;         asm volatile("s_waitcnt vmcnt(0)" ::: "memory");
;     }
;     __syncthreads();
.LBB0_609:
	s_cmp_lt_i32 s47, 7
	s_cbranch_scc1 .LBB0_626
	s_waitcnt vmcnt(0)
	v_cmp_eq_u32_e32 vcc, 0, v202
	s_waitcnt vmcnt(0) lgkmcnt(0)
	s_barrier
	s_and_saveexec_b64 s[0:1], vcc
	s_cbranch_execz .LBB0_625
	s_load_dwordx2 s[4:5], s[84:85], 0x90
	s_lshl_b32 s3, s98, 6
	v_mov_b32_e32 v0, s3
	v_mov_b32_e32 v2, 1
	s_waitcnt lgkmcnt(0)
	s_add_u32 s4, s4, 0x1400
	s_addc_u32 s5, s5, 0
	global_atomic_add v1, v0, v2, s[4:5] offset:128 sc0
	s_mul_i32 s6, s99, 5
	s_add_i32 s3, s6, -1
	s_lshl_b32 s6, s98, 6
	s_sub_u32 s6, s4, s6
	s_subb_u32 s7, s5, 0
	s_mul_i32 s4, s100, 5
	s_waitcnt vmcnt(0)
	v_cmp_ne_u32_e32 vcc, s3, v1
	s_cbranch_vccnz .Lsm5_wtop
	global_atomic_add v0, v2, s[6:7] offset:2176
